# up-GEMM epilogue conv+silu block re-scheduled for ILP (SSA rename + list schedule), same ops
# baseline (speedup 1.0000x reference)
.LBB0_738:
	s_or_b64 exec, exec, s[0:1]
	v_pk_fma_f32 v[46:47], v[142:143], v[186:187], v[146:147]
	v_mov_b32_dpp v48, v186 row_shr:1 row_mask:0xf bank_mask:0xf bound_ctrl:1
	v_mov_b32_dpp v49, v187 row_shr:1 row_mask:0xf bank_mask:0xf bound_ctrl:1
	v_mov_b32_dpp v186, v182 row_shr:1 row_mask:0xf bank_mask:0xf bound_ctrl:1
	v_pk_fma_f32 v[46:47], v[126:127], v[170:171], v[46:47]
	v_mov_b32_dpp v187, v183 row_shr:1 row_mask:0xf bank_mask:0xf bound_ctrl:1
	v_mov_b32_dpp v198, v170 row_shr:1 row_mask:0xf bank_mask:0xf bound_ctrl:1
	v_mov_b32_dpp v199, v171 row_shr:1 row_mask:0xf bank_mask:0xf bound_ctrl:1
	v_pk_fma_f32 v[46:47], v[122:123], v[158:159], v[46:47]
	v_pk_fma_f32 v[182:183], v[182:183], v[162:163], v[166:167]
	v_pk_fma_f32 v[200:201], v[184:185], v[164:165], v[168:169]
	v_pk_mul_f32 v[202:203], v[46:47], s[82:83] op_sel_hi:[1,0]
	v_pk_fma_f32 v[182:183], v[114:115], v[178:179], v[182:183]
	v_pk_fma_f32 v[182:183], v[110:111], v[194:195], v[182:183]
	v_pk_fma_f32 v[204:205], v[116:117], v[180:181], v[200:201]
	v_pk_fma_f32 v[200:201], v[112:113], v[196:197], v[204:205]
	v_exp_f32_e32 v204, v202
	v_exp_f32_e32 v205, v203
	s_nop 0
	v_pk_add_f32 v[202:203], v[204:205], 1.0 op_sel_hi:[1,0]
	v_rcp_f32_e32 v204, v202
	v_rcp_f32_e32 v205, v203
	s_nop 0
	v_pk_mul_f32 v[46:47], v[46:47], v[204:205]
	v_mov_b32_dpp v202, v178 row_shr:1 row_mask:0xf bank_mask:0xf bound_ctrl:1
	v_mov_b32_dpp v203, v179 row_shr:1 row_mask:0xf bank_mask:0xf bound_ctrl:1
	v_pk_mul_f32 v[182:183], v[182:183], v[46:47]
	v_pk_fma_f32 v[46:47], v[170:171], v[142:143], v[146:147]
	v_pk_fma_f32 v[46:47], v[126:127], v[158:159], v[46:47]
	v_pk_fma_f32 v[46:47], v[122:123], v[154:155], v[46:47]
	v_pk_mul_f32 v[170:171], v[46:47], s[82:83] op_sel_hi:[1,0]
	v_exp_f32_e32 v170, v170
	v_exp_f32_e32 v171, v171
	s_nop 0
	v_pk_add_f32 v[170:171], v[170:171], 1.0 op_sel_hi:[1,0]
	v_rcp_f32_e32 v170, v170
	v_rcp_f32_e32 v171, v171
	s_nop 0
	v_pk_mul_f32 v[46:47], v[46:47], v[170:171]
	v_pk_fma_f32 v[204:205], v[178:179], v[162:163], v[166:167]
	v_pk_fma_f32 v[178:179], v[194:195], v[114:115], v[204:205]
	v_pk_fma_f32 v[204:205], v[194:195], v[162:163], v[166:167]
	v_pk_fma_f32 v[194:195], v[110:111], v[190:191], v[178:179]
	v_pk_mul_f32 v[170:171], v[194:195], v[46:47]
	v_pk_fma_f32 v[178:179], v[180:181], v[164:165], v[168:169]
	v_pk_fma_f32 v[46:47], v[158:159], v[142:143], v[146:147]
	v_pk_fma_f32 v[158:159], v[196:197], v[116:117], v[178:179]
	v_pk_fma_f32 v[178:179], v[196:197], v[164:165], v[168:169]
	v_pk_fma_f32 v[46:47], v[154:155], v[126:127], v[46:47]
	v_pk_fma_f32 v[194:195], v[112:113], v[192:193], v[158:159]
	v_pk_fma_f32 v[158:159], v[192:193], v[116:117], v[178:179]
	v_pk_fma_f32 v[154:155], v[154:155], v[142:143], v[146:147]
	v_pk_fma_f32 v[46:47], v[122:123], v[48:49], v[46:47]
	v_pk_fma_f32 v[178:179], v[190:191], v[114:115], v[204:205]
	v_pk_fma_f32 v[196:197], v[190:191], v[162:163], v[166:167]
	v_pk_fma_f32 v[48:49], v[126:127], v[48:49], v[154:155]
	v_mov_b32_dpp v190, v98 row_shr:1 row_mask:0xf bank_mask:0xf bound_ctrl:1
	v_pk_fma_f32 v[48:49], v[122:123], v[198:199], v[48:49]
	v_pk_fma_f32 v[198:199], v[114:115], v[186:187], v[196:197]
	v_mov_b32_dpp v191, v99 row_shr:1 row_mask:0xf bank_mask:0xf bound_ctrl:1
	v_pk_mul_f32 v[154:155], v[48:49], s[82:83] op_sel_hi:[1,0]
	v_pk_fma_f32 v[196:197], v[110:111], v[202:203], v[198:199]
	v_pk_fma_f32 v[98:99], v[142:143], v[98:99], v[146:147]
	v_exp_f32_e32 v154, v154
	v_exp_f32_e32 v155, v155
	v_pk_mul_f32 v[198:199], v[46:47], s[82:83] op_sel_hi:[1,0]
	v_pk_fma_f32 v[98:99], v[126:127], v[94:95], v[98:99]
	v_mov_b32_dpp v202, v90 row_shr:1 row_mask:0xf bank_mask:0xf bound_ctrl:1
	v_pk_add_f32 v[154:155], v[154:155], 1.0 op_sel_hi:[1,0]
	v_mov_b32_dpp v203, v91 row_shr:1 row_mask:0xf bank_mask:0xf bound_ctrl:1
	v_rcp_f32_e32 v154, v154
	v_rcp_f32_e32 v155, v155
	v_pk_fma_f32 v[90:91], v[162:163], v[90:91], v[166:167]
	v_pk_mul_f32 v[48:49], v[48:49], v[154:155]
	v_pk_mul_f32 v[154:155], v[196:197], v[48:49]
	v_exp_f32_e32 v196, v198
	v_exp_f32_e32 v197, v199
	v_pk_fma_f32 v[48:49], v[144:145], v[100:101], v[148:149]
	v_pk_fma_f32 v[90:91], v[114:115], v[86:87], v[90:91]
	v_pk_fma_f32 v[198:199], v[110:111], v[186:187], v[178:179]
	v_pk_fma_f32 v[48:49], v[128:129], v[96:97], v[48:49]
	v_pk_add_f32 v[178:179], v[196:197], 1.0 op_sel_hi:[1,0]
	v_pk_fma_f32 v[90:91], v[110:111], v[174:175], v[90:91]
	v_pk_fma_f32 v[186:187], v[124:125], v[120:121], v[48:49]
	v_rcp_f32_e32 v196, v178
	v_rcp_f32_e32 v197, v179
	v_pk_fma_f32 v[48:49], v[122:123], v[118:119], v[98:99]
	v_mov_b32_dpp v178, v94 row_shr:1 row_mask:0xf bank_mask:0xf bound_ctrl:1
	v_pk_mul_f32 v[46:47], v[46:47], v[196:197]
	v_pk_mul_f32 v[98:99], v[48:49], s[82:83] op_sel_hi:[1,0]
	v_mov_b32_dpp v179, v95 row_shr:1 row_mask:0xf bank_mask:0xf bound_ctrl:1
	v_pk_mul_f32 v[46:47], v[198:199], v[46:47]
	v_exp_f32_e32 v98, v98
	v_exp_f32_e32 v99, v99
	v_pk_fma_f32 v[94:95], v[142:143], v[94:95], v[146:147]
	v_mov_b32_dpp v196, v86 row_shr:1 row_mask:0xf bank_mask:0xf bound_ctrl:1
	v_mov_b32_dpp v197, v87 row_shr:1 row_mask:0xf bank_mask:0xf bound_ctrl:1
	v_pk_fma_f32 v[198:199], v[192:193], v[164:165], v[168:169]
	v_pk_add_f32 v[98:99], v[98:99], 1.0 op_sel_hi:[1,0]
	v_pk_fma_f32 v[94:95], v[126:127], v[118:119], v[94:95]
	v_pk_fma_f32 v[86:87], v[162:163], v[86:87], v[166:167]
	v_rcp_f32_e32 v98, v98
	v_rcp_f32_e32 v99, v99
	v_pk_fma_f32 v[86:87], v[114:115], v[174:175], v[86:87]
	v_mov_b32_dpp v192, v184 row_shr:1 row_mask:0xf bank_mask:0xf bound_ctrl:1
	v_mov_b32_dpp v193, v185 row_shr:1 row_mask:0xf bank_mask:0xf bound_ctrl:1
	v_mov_b32_dpp v100, v100 row_shr:1 row_mask:0xf bank_mask:0xf bound_ctrl:1
	v_pk_mul_f32 v[48:49], v[48:49], v[98:99]
	v_pk_fma_f32 v[86:87], v[110:111], v[130:131], v[86:87]
	v_mov_b32_dpp v101, v101 row_shr:1 row_mask:0xf bank_mask:0xf bound_ctrl:1
	v_pk_mul_f32 v[90:91], v[90:91], v[48:49]
	v_pk_fma_f32 v[98:99], v[164:165], v[88:89], v[168:169]
	v_pk_fma_f32 v[48:49], v[144:145], v[96:97], v[148:149]
	v_pk_fma_f32 v[98:99], v[116:117], v[176:177], v[98:99]
	v_pk_fma_f32 v[48:49], v[128:129], v[120:121], v[48:49]
	v_mov_b32_dpp v96, v96 row_shr:1 row_mask:0xf bank_mask:0xf bound_ctrl:1
	v_mov_b32_dpp v97, v97 row_shr:1 row_mask:0xf bank_mask:0xf bound_ctrl:1
	v_pk_fma_f32 v[204:205], v[112:113], v[192:193], v[158:159]
	v_pk_fma_f32 v[158:159], v[116:117], v[192:193], v[198:199]
	v_pk_fma_f32 v[192:193], v[124:125], v[136:137], v[48:49]
	v_pk_fma_f32 v[48:49], v[122:123], v[134:135], v[94:95]
	v_pk_mul_f32 v[94:95], v[48:49], s[82:83] op_sel_hi:[1,0]
	v_exp_f32_e32 v94, v94
	v_exp_f32_e32 v95, v95
	s_nop 0
	v_pk_add_f32 v[94:95], v[94:95], 1.0 op_sel_hi:[1,0]
	v_rcp_f32_e32 v94, v94
	v_rcp_f32_e32 v95, v95
	s_nop 0
	v_pk_mul_f32 v[48:49], v[48:49], v[94:95]
	v_pk_fma_f32 v[94:95], v[142:143], v[118:119], v[146:147]
	v_pk_fma_f32 v[118:119], v[162:163], v[174:175], v[166:167]
	v_pk_fma_f32 v[174:175], v[112:113], v[132:133], v[98:99]
	v_pk_mul_f32 v[48:49], v[86:87], v[48:49]
	v_pk_fma_f32 v[86:87], v[144:145], v[120:121], v[148:149]
	v_pk_fma_f32 v[94:95], v[126:127], v[134:135], v[94:95]
	v_pk_fma_f32 v[120:121], v[164:165], v[132:133], v[168:169]
	v_pk_fma_f32 v[94:95], v[122:123], v[190:191], v[94:95]
	v_pk_mul_f32 v[98:99], v[94:95], s[82:83] op_sel_hi:[1,0]
	v_exp_f32_e32 v98, v98
	v_exp_f32_e32 v99, v99
	s_nop 0
	v_pk_add_f32 v[98:99], v[98:99], 1.0 op_sel_hi:[1,0]
	v_rcp_f32_e32 v98, v98
	v_rcp_f32_e32 v99, v99
	s_nop 0
	v_pk_mul_f32 v[94:95], v[94:95], v[98:99]
	v_pk_fma_f32 v[198:199], v[128:129], v[136:137], v[86:87]
	v_pk_fma_f32 v[86:87], v[164:165], v[176:177], v[168:169]
	v_pk_fma_f32 v[206:207], v[144:145], v[136:137], v[148:149]
	v_pk_fma_f32 v[136:137], v[124:125], v[100:101], v[198:199]
	v_pk_fma_f32 v[100:101], v[128:129], v[100:101], v[206:207]
	v_pk_fma_f32 v[100:101], v[124:125], v[96:97], v[100:101]
	v_pk_mul_f32 v[96:97], v[100:101], s[82:83] op_sel_hi:[1,0]
	v_pk_fma_f32 v[198:199], v[116:117], v[132:133], v[86:87]
	v_pk_fma_f32 v[86:87], v[114:115], v[130:131], v[118:119]
	v_pk_fma_f32 v[118:119], v[162:163], v[130:131], v[166:167]
	v_pk_fma_f32 v[86:87], v[110:111], v[202:203], v[86:87]
	v_pk_fma_f32 v[130:131], v[172:173], v[144:145], v[148:149]
	v_pk_fma_f32 v[114:115], v[114:115], v[202:203], v[118:119]
	v_pk_mul_f32 v[86:87], v[86:87], v[94:95]
	v_pk_fma_f32 v[132:133], v[128:129], v[160:161], v[130:131]
	v_pk_fma_f32 v[110:111], v[110:111], v[196:197], v[114:115]
	v_pk_fma_f32 v[94:95], v[142:143], v[134:135], v[146:147]
	v_pk_fma_f32 v[130:131], v[124:125], v[156:157], v[132:133]
	v_mov_b32_dpp v114, v188 row_shr:1 row_mask:0xf bank_mask:0xf bound_ctrl:1
	v_pk_fma_f32 v[94:95], v[126:127], v[190:191], v[94:95]
	v_mov_b32_dpp v115, v189 row_shr:1 row_mask:0xf bank_mask:0xf bound_ctrl:1
	v_pk_mul_f32 v[126:127], v[130:131], s[82:83] op_sel_hi:[1,0]
	v_pk_fma_f32 v[94:95], v[122:123], v[178:179], v[94:95]
	v_mov_b32_dpp v118, v172 row_shr:1 row_mask:0xf bank_mask:0xf bound_ctrl:1
	v_exp_f32_e32 v122, v126
	v_pk_mul_f32 v[98:99], v[94:95], s[82:83] op_sel_hi:[1,0]
	v_exp_f32_e32 v123, v127
	v_mov_b32_dpp v119, v173 row_shr:1 row_mask:0xf bank_mask:0xf bound_ctrl:1
	v_exp_f32_e32 v98, v98
	v_exp_f32_e32 v99, v99
	v_mov_b32_dpp v126, v180 row_shr:1 row_mask:0xf bank_mask:0xf bound_ctrl:1
	v_mov_b32_dpp v127, v181 row_shr:1 row_mask:0xf bank_mask:0xf bound_ctrl:1
	v_pk_fma_f32 v[132:133], v[164:165], v[92:93], v[168:169]
	v_pk_fma_f32 v[134:135], v[112:113], v[126:127], v[158:159]
	v_pk_add_f32 v[98:99], v[98:99], 1.0 op_sel_hi:[1,0]
	v_pk_fma_f32 v[126:127], v[116:117], v[88:89], v[132:133]
	v_pk_fma_f32 v[132:133], v[160:161], v[144:145], v[148:149]
	v_rcp_f32_e32 v98, v98
	v_rcp_f32_e32 v99, v99
	v_pk_fma_f32 v[142:143], v[156:157], v[144:145], v[148:149]
	v_pk_fma_f32 v[158:159], v[156:157], v[128:129], v[132:133]
	v_pk_fma_f32 v[132:133], v[112:113], v[176:177], v[126:127]
	v_pk_mul_f32 v[94:95], v[94:95], v[98:99]
	v_pk_fma_f32 v[126:127], v[124:125], v[114:115], v[158:159]
	v_exp_f32_e32 v158, v96
	v_pk_fma_f32 v[98:99], v[144:145], v[188:189], v[148:149]
	v_pk_mul_f32 v[94:95], v[110:111], v[94:95]
	v_pk_fma_f32 v[114:115], v[128:129], v[114:115], v[142:143]
	v_pk_fma_f32 v[98:99], v[128:129], v[172:173], v[98:99]
	v_pk_mul_f32 v[128:129], v[126:127], s[82:83] op_sel_hi:[1,0]
	v_pk_fma_f32 v[118:119], v[124:125], v[118:119], v[114:115]
	v_pk_fma_f32 v[98:99], v[124:125], v[160:161], v[98:99]
	v_exp_f32_e32 v124, v128
	v_exp_f32_e32 v125, v129
	v_pk_mul_f32 v[110:111], v[98:99], s[82:83] op_sel_hi:[1,0]
	v_pk_mul_f32 v[114:115], v[118:119], s[82:83] op_sel_hi:[1,0]
	v_mov_b32_dpp v128, v88 row_shr:1 row_mask:0xf bank_mask:0xf bound_ctrl:1
	v_exp_f32_e32 v110, v110
	v_exp_f32_e32 v111, v111
	v_exp_f32_e32 v142, v114
	v_pk_add_f32 v[144:145], v[124:125], 1.0 op_sel_hi:[1,0]
	v_exp_f32_e32 v143, v115
	v_pk_add_f32 v[110:111], v[110:111], 1.0 op_sel_hi:[1,0]
	v_rcp_f32_e32 v124, v144
	v_rcp_f32_e32 v125, v145
	v_rcp_f32_e32 v110, v110
	v_rcp_f32_e32 v111, v111
	v_pk_add_f32 v[144:145], v[142:143], 1.0 op_sel_hi:[1,0]
	v_pk_mul_f32 v[114:115], v[126:127], v[124:125]
	v_mov_b32_dpp v129, v89 row_shr:1 row_mask:0xf bank_mask:0xf bound_ctrl:1
	v_pk_mul_f32 v[98:99], v[98:99], v[110:111]
	v_rcp_f32_e32 v124, v144
	v_rcp_f32_e32 v125, v145
	v_pk_add_f32 v[110:111], v[122:123], 1.0 op_sel_hi:[1,0]
	v_exp_f32_e32 v159, v97
	v_mov_b32_dpp v122, v102 row_shr:1 row_mask:0xf bank_mask:0xf bound_ctrl:1
	v_rcp_f32_e32 v110, v110
	v_rcp_f32_e32 v111, v111
	v_pk_mul_f32 v[118:119], v[118:119], v[124:125]
	v_mov_b32_dpp v124, v92 row_shr:1 row_mask:0xf bank_mask:0xf bound_ctrl:1
	v_pk_mul_f32 v[126:127], v[186:187], s[82:83] op_sel_hi:[1,0]
	v_pk_mul_f32 v[110:111], v[130:131], v[110:111]
	v_pk_mul_f32 v[118:119], v[134:135], v[118:119]
	v_mov_b32_dpp v125, v93 row_shr:1 row_mask:0xf bank_mask:0xf bound_ctrl:1
	v_exp_f32_e32 v130, v126
	v_exp_f32_e32 v131, v127
	v_pk_fma_f32 v[126:127], v[116:117], v[124:125], v[120:121]
	v_pk_fma_f32 v[116:117], v[112:113], v[124:125], v[198:199]
	v_pk_mul_f32 v[120:121], v[192:193], s[82:83] op_sel_hi:[1,0]
	v_pk_fma_f32 v[124:125], v[112:113], v[128:129], v[126:127]
	v_pk_add_f32 v[92:93], v[130:131], 1.0 op_sel_hi:[1,0]
	v_exp_f32_e32 v112, v120
	v_exp_f32_e32 v113, v121
	v_rcp_f32_e32 v92, v92
	v_rcp_f32_e32 v93, v93
	v_mov_b32_dpp v123, v103 row_shr:1 row_mask:0xf bank_mask:0xf bound_ctrl:1
	v_pk_mul_f32 v[120:121], v[136:137], s[82:83] op_sel_hi:[1,0]
	v_pk_fma_f32 v[102:103], v[102:103], v[26:27], v[30:31]
	v_pk_mul_f32 v[88:89], v[186:187], v[92:93]
	v_exp_f32_e32 v126, v120
	v_pk_fma_f32 v[102:103], v[78:79], v[6:7], v[102:103]
	v_pk_add_f32 v[92:93], v[112:113], 1.0 op_sel_hi:[1,0]
	v_exp_f32_e32 v127, v121
	v_pk_fma_f32 v[102:103], v[150:151], v[2:3], v[102:103]
	v_mov_b32_dpp v112, v78 row_shr:1 row_mask:0xf bank_mask:0xf bound_ctrl:1
	v_mov_b32_dpp v113, v79 row_shr:1 row_mask:0xf bank_mask:0xf bound_ctrl:1
	v_pk_fma_f32 v[120:121], v[36:37], v[28:29], v[32:33]
	v_pk_add_f32 v[128:129], v[126:127], 1.0 op_sel_hi:[1,0]
	v_pk_fma_f32 v[78:79], v[78:79], v[26:27], v[30:31]
	v_pk_add_f32 v[126:127], v[158:159], 1.0 op_sel_hi:[1,0]
	v_rcp_f32_e32 v130, v128
	v_rcp_f32_e32 v131, v129
	v_pk_fma_f32 v[78:79], v[150:151], v[6:7], v[78:79]
	v_mov_b32_dpp v128, v38 row_shr:1 row_mask:0xf bank_mask:0xf bound_ctrl:1
	v_rcp_f32_e32 v134, v126
	v_pk_fma_f32 v[78:79], v[138:139], v[2:3], v[78:79]
	v_pk_mul_f32 v[96:97], v[136:137], v[130:131]
	v_rcp_f32_e32 v135, v127
	v_mov_b32_dpp v129, v39 row_shr:1 row_mask:0xf bank_mask:0xf bound_ctrl:1
	v_pk_fma_f32 v[126:127], v[104:105], v[28:29], v[32:33]
	v_pk_fma_f32 v[130:131], v[40:41], v[8:9], v[120:121]
	v_pk_mul_f32 v[100:101], v[100:101], v[134:135]
	v_mov_b32_dpp v120, v82 row_shr:1 row_mask:0xf bank_mask:0xf bound_ctrl:1
	v_mov_b32_dpp v134, v106 row_shr:1 row_mask:0xf bank_mask:0xf bound_ctrl:1
	v_mov_b32_dpp v135, v107 row_shr:1 row_mask:0xf bank_mask:0xf bound_ctrl:1
	v_pk_mul_f32 v[100:101], v[124:125], v[100:101]
	v_pk_fma_f32 v[124:125], v[106:107], v[18:19], v[22:23]
	v_mov_b32_dpp v121, v83 row_shr:1 row_mask:0xf bank_mask:0xf bound_ctrl:1
	v_pk_fma_f32 v[106:107], v[80:81], v[8:9], v[126:127]
	v_pk_fma_f32 v[126:127], v[82:83], v[14:15], v[124:125]
	v_pk_fma_f32 v[124:125], v[80:81], v[28:29], v[32:33]
	v_pk_fma_f32 v[136:137], v[152:153], v[4:5], v[106:107]
	v_pk_fma_f32 v[82:83], v[82:83], v[18:19], v[22:23]
	v_pk_fma_f32 v[106:107], v[66:67], v[10:11], v[126:127]
	v_pk_fma_f32 v[126:127], v[152:153], v[8:9], v[124:125]
	v_pk_fma_f32 v[82:83], v[66:67], v[14:15], v[82:83]
	v_pk_mul_f32 v[124:125], v[106:107], s[82:83] op_sel_hi:[1,0]
	v_rcp_f32_e32 v92, v92
	v_pk_fma_f32 v[82:83], v[54:55], v[10:11], v[82:83]
	v_exp_f32_e32 v142, v124
	v_exp_f32_e32 v143, v125
	v_pk_fma_f32 v[66:67], v[66:67], v[18:19], v[22:23]
	v_pk_mul_f32 v[124:125], v[82:83], s[82:83] op_sel_hi:[1,0]
	v_rcp_f32_e32 v93, v93
	v_pk_fma_f32 v[66:67], v[54:55], v[14:15], v[66:67]
	v_pk_add_f32 v[144:145], v[142:143], 1.0 op_sel_hi:[1,0]
	v_exp_f32_e32 v142, v124
	v_pk_fma_f32 v[66:67], v[10:11], v[134:135], v[66:67]
	v_rcp_f32_e32 v158, v144
	v_rcp_f32_e32 v159, v145
	v_pk_fma_f32 v[54:55], v[54:55], v[18:19], v[22:23]
	v_exp_f32_e32 v143, v125
	v_mov_b32_dpp v124, v36 row_shr:1 row_mask:0xf bank_mask:0xf bound_ctrl:1
	v_pk_fma_f32 v[54:55], v[14:15], v[134:135], v[54:55]
	v_pk_mul_f32 v[134:135], v[106:107], v[158:159]
	v_pk_add_f32 v[106:107], v[142:143], 1.0 op_sel_hi:[1,0]
	v_mov_b32_dpp v125, v37 row_shr:1 row_mask:0xf bank_mask:0xf bound_ctrl:1
	v_pk_mul_f32 v[102:103], v[102:103], v[134:135]
	v_rcp_f32_e32 v36, v106
	v_rcp_f32_e32 v37, v107
	v_pk_fma_f32 v[106:107], v[140:141], v[4:5], v[126:127]
	v_pk_fma_f32 v[126:127], v[152:153], v[28:29], v[32:33]
	v_pk_mul_f32 v[98:99], v[200:201], v[98:99]
	v_pk_mul_f32 v[82:83], v[82:83], v[36:37]
	v_pk_fma_f32 v[36:37], v[150:151], v[26:27], v[30:31]
	v_pk_fma_f32 v[134:135], v[140:141], v[8:9], v[126:127]
	v_pk_mul_f32 v[78:79], v[78:79], v[82:83]
	v_pk_fma_f32 v[126:127], v[138:139], v[6:7], v[36:37]
	v_pk_mul_f32 v[110:111], v[194:195], v[110:111]
	v_pk_mul_f32 v[82:83], v[66:67], s[82:83] op_sel_hi:[1,0]
	v_pk_fma_f32 v[36:37], v[2:3], v[122:123], v[126:127]
	v_pk_mul_f32 v[114:115], v[204:205], v[114:115]
	v_exp_f32_e32 v82, v82
	v_exp_f32_e32 v83, v83
	v_pk_mul_f32 v[92:93], v[192:193], v[92:93]
	v_mov_b32_e32 v0, v46
	v_pk_fma_f32 v[126:127], v[138:139], v[26:27], v[30:31]
	v_pk_add_f32 v[82:83], v[82:83], 1.0 op_sel_hi:[1,0]
	v_mov_b32_e32 v46, v48
	v_pk_fma_f32 v[142:143], v[6:7], v[122:123], v[126:127]
	v_rcp_f32_e32 v82, v82
	v_rcp_f32_e32 v83, v83
	v_mov_b32_dpp v122, v34 row_shr:1 row_mask:0xf bank_mask:0xf bound_ctrl:1
	v_pk_fma_f32 v[126:127], v[2:3], v[112:113], v[142:143]
	v_mov_b32_dpp v123, v35 row_shr:1 row_mask:0xf bank_mask:0xf bound_ctrl:1
	v_mov_b32_dpp v112, v58 row_shr:1 row_mask:0xf bank_mask:0xf bound_ctrl:1
	v_pk_mul_f32 v[66:67], v[66:67], v[82:83]
	v_pk_fma_f32 v[34:35], v[34:35], v[26:27], v[30:31]
	v_mov_b32_dpp v142, v42 row_shr:1 row_mask:0xf bank_mask:0xf bound_ctrl:1
	v_pk_fma_f32 v[82:83], v[10:11], v[120:121], v[54:55]
	v_pk_mul_f32 v[66:67], v[36:37], v[66:67]
	v_pk_fma_f32 v[34:35], v[38:39], v[6:7], v[34:35]
	v_pk_mul_f32 v[54:55], v[82:83], s[82:83] op_sel_hi:[1,0]
	v_mov_b32_dpp v143, v43 row_shr:1 row_mask:0xf bank_mask:0xf bound_ctrl:1
	v_pk_fma_f32 v[34:35], v[74:75], v[2:3], v[34:35]
	v_exp_f32_e32 v36, v54
	v_exp_f32_e32 v37, v55
	v_pk_fma_f32 v[42:43], v[42:43], v[18:19], v[22:23]
	v_mov_b32_dpp v113, v59 row_shr:1 row_mask:0xf bank_mask:0xf bound_ctrl:1
	v_pk_fma_f32 v[38:39], v[38:39], v[26:27], v[30:31]
	v_pk_add_f32 v[120:121], v[36:37], 1.0 op_sel_hi:[1,0]
	v_pk_fma_f32 v[42:43], v[58:59], v[14:15], v[42:43]
	v_pk_fma_f32 v[38:39], v[74:75], v[6:7], v[38:39]
	v_rcp_f32_e32 v36, v120
	v_rcp_f32_e32 v37, v121
	v_pk_fma_f32 v[42:43], v[50:51], v[10:11], v[42:43]
	v_pk_fma_f32 v[38:39], v[62:63], v[2:3], v[38:39]
	v_pk_fma_f32 v[120:121], v[74:75], v[26:27], v[30:31]
	v_pk_mul_f32 v[82:83], v[82:83], v[36:37]
	v_pk_mul_f32 v[36:37], v[42:43], s[82:83] op_sel_hi:[1,0]
	v_pk_fma_f32 v[26:27], v[62:63], v[26:27], v[30:31]
	v_pk_mul_f32 v[82:83], v[126:127], v[82:83]
	v_exp_f32_e32 v74, v36
	v_exp_f32_e32 v75, v37
	v_pk_fma_f32 v[36:37], v[62:63], v[6:7], v[120:121]
	v_pk_fma_f32 v[30:31], v[84:85], v[20:21], v[24:25]
	v_pk_fma_f32 v[62:63], v[76:77], v[4:5], v[130:131]
	v_pk_add_f32 v[120:121], v[74:75], 1.0 op_sel_hi:[1,0]
	v_pk_fma_f32 v[6:7], v[6:7], v[122:123], v[26:27]
	v_pk_fma_f32 v[74:75], v[2:3], v[122:123], v[36:37]
	v_rcp_f32_e32 v36, v120
	v_rcp_f32_e32 v37, v121
	v_pk_fma_f32 v[2:3], v[2:3], v[128:129], v[6:7]
	v_pk_fma_f32 v[30:31], v[68:69], v[16:17], v[30:31]
	v_pk_fma_f32 v[120:121], v[40:41], v[28:29], v[32:33]
	v_pk_mul_f32 v[42:43], v[42:43], v[36:37]
	v_pk_fma_f32 v[30:31], v[56:57], v[12:13], v[30:31]
	v_pk_fma_f32 v[36:37], v[140:141], v[28:29], v[32:33]
	v_pk_mul_f32 v[42:43], v[34:35], v[42:43]
	v_pk_fma_f32 v[122:123], v[76:77], v[8:9], v[120:121]
	v_pk_fma_f32 v[120:121], v[76:77], v[28:29], v[32:33]
	v_pk_fma_f32 v[34:35], v[58:59], v[18:19], v[22:23]
	v_mov_b32_dpp v26, v84 row_shr:1 row_mask:0xf bank_mask:0xf bound_ctrl:1
	v_mov_b32_dpp v27, v85 row_shr:1 row_mask:0xf bank_mask:0xf bound_ctrl:1
	v_pk_fma_f32 v[58:59], v[64:65], v[4:5], v[122:123]
	v_pk_fma_f32 v[34:35], v[50:51], v[14:15], v[34:35]
	v_mov_b32_dpp v76, v80 row_shr:1 row_mask:0xf bank_mask:0xf bound_ctrl:1
	v_mov_b32_dpp v77, v81 row_shr:1 row_mask:0xf bank_mask:0xf bound_ctrl:1
	v_mov_b32_dpp v122, v40 row_shr:1 row_mask:0xf bank_mask:0xf bound_ctrl:1
	v_pk_fma_f32 v[34:35], v[70:71], v[10:11], v[34:35]
	v_mov_b32_dpp v123, v41 row_shr:1 row_mask:0xf bank_mask:0xf bound_ctrl:1
	v_mov_b32_e32 v48, v86
	v_pk_fma_f32 v[40:41], v[56:57], v[20:21], v[24:25]
	v_pk_mul_f32 v[126:127], v[34:35], s[82:83] op_sel_hi:[1,0]
	v_mov_b32_e32 v86, v95
	v_mov_b32_dpp v128, v60 row_shr:1 row_mask:0xf bank_mask:0xf bound_ctrl:1
	v_mov_b32_dpp v129, v61 row_shr:1 row_mask:0xf bank_mask:0xf bound_ctrl:1
	v_exp_f32_e32 v130, v126
	v_exp_f32_e32 v131, v127
	v_mov_b32_e32 v95, v98
	v_pk_fma_f32 v[126:127], v[60:61], v[20:21], v[24:25]
	v_mov_b32_e32 v98, v110
	v_pk_add_f32 v[144:145], v[130:131], 1.0 op_sel_hi:[1,0]
	v_mov_b32_e32 v110, v115
	v_pk_fma_f32 v[130:131], v[52:53], v[16:17], v[126:127]
	v_rcp_f32_e32 v126, v144
	v_rcp_f32_e32 v127, v145
	v_mov_b32_e32 v115, v118
	v_pk_fma_f32 v[144:145], v[72:73], v[12:13], v[130:131]
	v_pk_mul_f32 v[34:35], v[34:35], v[126:127]
	v_pk_mul_f32 v[126:127], v[144:145], s[82:83] op_sel_hi:[1,0]
	v_pk_mul_f32 v[34:35], v[38:39], v[34:35]
	v_exp_f32_e32 v130, v126
	v_exp_f32_e32 v131, v127
	v_pk_fma_f32 v[38:39], v[50:51], v[18:19], v[22:23]
	v_pk_mul_f32 v[88:89], v[132:133], v[88:89]
	v_pk_fma_f32 v[18:19], v[70:71], v[18:19], v[22:23]
	v_pk_fma_f32 v[38:39], v[70:71], v[14:15], v[38:39]
	v_pk_mul_f32 v[92:93], v[174:175], v[92:93]
	v_pk_fma_f32 v[14:15], v[14:15], v[142:143], v[18:19]
	v_pk_fma_f32 v[38:39], v[10:11], v[142:143], v[38:39]
	v_pk_fma_f32 v[18:19], v[10:11], v[112:113], v[14:15]
	v_pk_mul_f32 v[50:51], v[38:39], s[82:83] op_sel_hi:[1,0]
	v_pk_mul_f32 v[96:97], v[116:117], v[96:97]
	v_pk_fma_f32 v[14:15], v[64:65], v[28:29], v[32:33]
	v_pk_mul_f32 v[10:11], v[18:19], s[82:83] op_sel_hi:[1,0]
	v_exp_f32_e32 v50, v50
	v_pk_mul_f32 v[32:33], v[30:31], s[82:83] op_sel_hi:[1,0]
	v_exp_f32_e32 v22, v10
	v_exp_f32_e32 v23, v11
	v_exp_f32_e32 v32, v32
	v_exp_f32_e32 v33, v33
	v_exp_f32_e32 v51, v51
	v_pk_add_f32 v[22:23], v[22:23], 1.0 op_sel_hi:[1,0]
	v_mov_b32_dpp v28, v104 row_shr:1 row_mask:0xf bank_mask:0xf bound_ctrl:1
	v_mov_b32_dpp v29, v105 row_shr:1 row_mask:0xf bank_mask:0xf bound_ctrl:1
	v_mov_b32_e32 v54, v66
	v_rcp_f32_e32 v22, v22
	v_rcp_f32_e32 v23, v23
	v_pk_add_f32 v[50:51], v[50:51], 1.0 op_sel_hi:[1,0]
	v_pk_fma_f32 v[112:113], v[4:5], v[28:29], v[134:135]
	v_mov_b32_e32 v55, v83
	v_pk_mul_f32 v[6:7], v[18:19], v[22:23]
	v_rcp_f32_e32 v116, v50
	v_rcp_f32_e32 v117, v51
	v_mov_b32_dpp v22, v108 row_shr:1 row_mask:0xf bank_mask:0xf bound_ctrl:1
	v_pk_mul_f32 v[2:3], v[2:3], v[6:7]
	v_mov_b32_dpp v23, v109 row_shr:1 row_mask:0xf bank_mask:0xf bound_ctrl:1
	v_pk_fma_f32 v[28:29], v[8:9], v[28:29], v[36:37]
	v_pk_fma_f32 v[6:7], v[108:109], v[20:21], v[24:25]
	v_pk_fma_f32 v[50:51], v[64:65], v[8:9], v[120:121]
	v_pk_fma_f32 v[28:29], v[4:5], v[76:77], v[28:29]
	v_pk_fma_f32 v[6:7], v[84:85], v[16:17], v[6:7]
	v_pk_fma_f32 v[8:9], v[8:9], v[124:125], v[14:15]
	v_pk_mul_f32 v[38:39], v[38:39], v[116:117]
	v_pk_fma_f32 v[6:7], v[68:69], v[12:13], v[6:7]
	v_pk_fma_f32 v[50:51], v[4:5], v[124:125], v[50:51]
	v_pk_mul_f32 v[38:39], v[74:75], v[38:39]
	v_pk_mul_f32 v[18:19], v[6:7], s[82:83] op_sel_hi:[1,0]
	v_pk_fma_f32 v[4:5], v[4:5], v[122:123], v[8:9]
	v_mov_b32_e32 v10, v38
	v_exp_f32_e32 v18, v18
	v_exp_f32_e32 v19, v19
	v_pk_fma_f32 v[36:37], v[52:53], v[20:21], v[24:25]
	v_pk_add_f32 v[18:19], v[18:19], 1.0 op_sel_hi:[1,0]
	v_pk_fma_f32 v[64:65], v[72:73], v[16:17], v[36:37]
	v_rcp_f32_e32 v18, v18
	v_rcp_f32_e32 v19, v19
	s_nop 0
	v_pk_mul_f32 v[6:7], v[6:7], v[18:19]
	v_pk_add_f32 v[18:19], v[32:33], 1.0 op_sel_hi:[1,0]
	v_pk_mul_f32 v[6:7], v[136:137], v[6:7]
	v_rcp_f32_e32 v18, v18
	v_rcp_f32_e32 v19, v19
	s_nop 0
	v_pk_mul_f32 v[18:19], v[30:31], v[18:19]
	v_pk_fma_f32 v[30:31], v[68:69], v[20:21], v[24:25]
	v_pk_mul_f32 v[18:19], v[106:107], v[18:19]
	v_pk_fma_f32 v[30:31], v[56:57], v[16:17], v[30:31]
	v_mov_b32_e32 v11, v18
	v_pk_fma_f32 v[30:31], v[12:13], v[22:23], v[30:31]
	v_pk_fma_f32 v[22:23], v[16:17], v[22:23], v[40:41]
	v_pk_mul_f32 v[32:33], v[30:31], s[82:83] op_sel_hi:[1,0]
	v_pk_fma_f32 v[22:23], v[12:13], v[26:27], v[22:23]
	v_exp_f32_e32 v32, v32
	v_exp_f32_e32 v33, v33
	v_pk_mul_f32 v[26:27], v[22:23], s[82:83] op_sel_hi:[1,0]
	v_exp_f32_e32 v36, v26
	v_pk_add_f32 v[32:33], v[32:33], 1.0 op_sel_hi:[1,0]
	v_exp_f32_e32 v37, v27
	v_rcp_f32_e32 v32, v32
	v_rcp_f32_e32 v33, v33
	s_nop 0
	v_pk_mul_f32 v[26:27], v[30:31], v[32:33]
	v_pk_add_f32 v[30:31], v[36:37], 1.0 op_sel_hi:[1,0]
	v_mov_b32_dpp v32, v44 row_shr:1 row_mask:0xf bank_mask:0xf bound_ctrl:1
	v_mov_b32_dpp v33, v45 row_shr:1 row_mask:0xf bank_mask:0xf bound_ctrl:1
	v_pk_mul_f32 v[26:27], v[112:113], v[26:27]
	v_rcp_f32_e32 v30, v30
	v_rcp_f32_e32 v31, v31
	v_pk_fma_f32 v[36:37], v[12:13], v[32:33], v[64:65]
	v_pk_mul_f32 v[22:23], v[22:23], v[30:31]
	v_pk_mul_f32 v[30:31], v[28:29], v[22:23]
	v_pk_fma_f32 v[22:23], v[44:45], v[20:21], v[24:25]
	v_pk_fma_f32 v[22:23], v[60:61], v[16:17], v[22:23]
	v_pk_fma_f32 v[20:21], v[72:73], v[20:21], v[24:25]
	v_pk_fma_f32 v[22:23], v[52:53], v[12:13], v[22:23]
	v_pk_fma_f32 v[16:17], v[16:17], v[32:33], v[20:21]
	v_pk_mul_f32 v[28:29], v[22:23], s[82:83] op_sel_hi:[1,0]
	v_pk_fma_f32 v[16:17], v[12:13], v[128:129], v[16:17]
	v_pk_mul_f32 v[52:53], v[36:37], s[82:83] op_sel_hi:[1,0]
	v_exp_f32_e32 v28, v28
	v_exp_f32_e32 v29, v29
	v_pk_mul_f32 v[12:13], v[16:17], s[82:83] op_sel_hi:[1,0]
	v_exp_f32_e32 v52, v52
	v_exp_f32_e32 v53, v53
	v_pk_add_f32 v[28:29], v[28:29], 1.0 op_sel_hi:[1,0]
	v_exp_f32_e32 v20, v12
	v_exp_f32_e32 v21, v13
	v_rcp_f32_e32 v28, v28
	v_rcp_f32_e32 v29, v29
	v_pk_add_f32 v[52:53], v[52:53], 1.0 op_sel_hi:[1,0]
	v_pk_add_f32 v[20:21], v[20:21], 1.0 op_sel_hi:[1,0]
	v_pk_mul_f32 v[22:23], v[22:23], v[28:29]
	v_rcp_f32_e32 v20, v20
	v_rcp_f32_e32 v21, v21
	v_pk_add_f32 v[28:29], v[130:131], 1.0 op_sel_hi:[1,0]
	v_pk_mul_f32 v[22:23], v[62:63], v[22:23]
	v_rcp_f32_e32 v52, v52
	v_rcp_f32_e32 v28, v28
	v_rcp_f32_e32 v29, v29
	v_rcp_f32_e32 v53, v53
	v_mov_b32_e32 v18, v22
	v_pk_mul_f32 v[8:9], v[16:17], v[20:21]
	v_pk_mul_f32 v[28:29], v[144:145], v[28:29]
	v_pk_mul_f32 v[12:13], v[36:37], v[52:53]
	v_pk_mul_f32 v[8:9], v[4:5], v[8:9]
	v_pk_mul_f32 v[28:29], v[58:59], v[28:29]
	v_pk_mul_f32 v[12:13], v[50:51], v[12:13]
	v_mov_b32_e32 v14, v8
	v_mov_b32_e32 v22, v29
	s_mov_b32 s0, 0
	s_nop 0
	v_mbcnt_lo_u32_b32 v4, -1, s0
	v_mbcnt_hi_u32_b32 v4, -1, v4
	v_and_b32_e32 v5, 15, v4
	v_ashrrev_i32_e32 v4, 1, v4
	v_and_b32_e32 v4, -8, v4
	v_add_u32_e32 v4, s19, v4
	v_cmp_ne_u32_e32 vcc, 0, v5
	v_lshl_or_b32 v8, v5, 2, s21
	v_ashrrev_i32_e32 v5, 31, v4
	v_lshlrev_b64 v[4:5], 1, v[4:5]
	s_and_saveexec_b64 s[0:1], vcc
	s_cbranch_execz .LBB0_740
	v_mov_b64_e32 v[16:17], s[12:13]
	v_or_b32_e32 v15, 1, v8
	v_mad_i64_i32 v[20:21], s[2:3], v8, s94, v[16:17]
	v_mad_i64_i32 v[16:17], s[2:3], v15, s94, v[16:17]
	v_cvt_pk_bf16_f32 v50, v154, v155
	v_cvt_pk_bf16_f32 v51, v115, v119
	v_cvt_pk_bf16_f32 v52, v82, v55
	v_cvt_pk_bf16_f32 v53, v30, v31
	v_lshl_add_u64 v[20:21], v[20:21], 0, v[4:5]
	v_cvt_pk_bf16_f32 v30, v0, v47
	v_cvt_pk_bf16_f32 v31, v114, v110
	v_cvt_pk_bf16_f32 v32, v54, v67
	v_cvt_pk_bf16_f32 v33, v26, v27
	v_lshl_add_u64 v[16:17], v[16:17], 0, v[4:5]
	global_store_dwordx4 v[20:21], v[50:53], off
	global_store_dwordx4 v[16:17], v[30:33], off
